# speedup vs baseline: 1.0188x; 1.0107x over previous
; __device__ __forceinline__ float bfs(short h) { return __uint_as_float(((unsigned)(u16)h) << 16); }
; __device__ __forceinline__ void phase_att_conv(PP p, const int g_wid, int layer) {
;     ...
;     for (int task = tid; task < 1344; task += 512) {
;       int jj = task >> 2, i0 = (task & 3) * 8, j = j0 + jj;
;       bf16x8 o1, o2;
;       if (j >= 0 && j < L) {
;         const u16* kp = Pac + (long)(base + j) * 2304 + 2048 + kh * 64 + i0;
;         bf16x8 a = *reinterpret_cast<const bf16x8*>(kp), b = *reinterpret_cast<const bf16x8*>(kp + 32);
;         const float2* cs = p->sincos + j * 64 + 2 * i0;
;         float t1[8], t2[8];
; #pragma unroll
;         for (int i = 0; i < 8; ++i) {
;           float2 c = cs[2 * i];
;           float x1 = bfs(a[i]), x2 = bfs(b[i]);
;           t1[i] = x1 * c.x - x2 * c.y;
;           t2[i] = x2 * c.x + x1 * c.y;
;         }
;         o1 = pack8(t1); o2 = pack8(t2);
.LBB0_287:
	v_ashrrev_i32_e32 v14, 2, v13
	v_and_b32_e32 v10, 24, v12
	v_add_u32_e32 v11, s7, v14
	v_cmp_gt_u32_e32 vcc, s3, v11
	v_mov_b32_e32 v6, 0
	v_lshlrev_b32_e32 v0, 1, v10
	v_mov_b32_e32 v7, 0
	v_mov_b32_e32 v8, 0
	v_mov_b32_e32 v9, 0
	v_mov_b32_e32 v2, 0
	v_mov_b32_e32 v3, 0
	v_mov_b32_e32 v4, 0
	v_mov_b32_e32 v5, 0
	s_and_saveexec_b64 s[10:11], vcc
	s_cbranch_execz .LBB0_286
	v_readlane_b32 s14, v254, 54
	v_readlane_b32 s15, v254, 55
	v_add_u32_e32 v4, s2, v11
	s_movk_i32 s13, 0x1200
	v_mov_b64_e32 v[2:3], s[14:15]
	v_mad_i64_i32 v[2:3], s[14:15], v4, s13, v[2:3]
	v_lshl_add_u64 v[2:3], v[2:3], 0, s[54:55]
	v_lshl_add_u64 v[2:3], v[2:3], 0, v[0:1]
	v_lshl_add_u64 v[4:5], v[2:3], 0, s[16:17]
	v_add_co_u32_e32 v2, vcc, 0x1000, v2
	v_readlane_b32 s14, v254, 0
	s_nop 0
	v_addc_co_u32_e32 v3, vcc, 0, v3, vcc
	v_readlane_b32 s15, v254, 1
	global_load_dwordx4 v[16:19], v[2:3], off
	global_load_dwordx4 v[20:23], v[4:5], off offset:64
	s_load_dwordx2 s[14:15], s[14:15], 0xc0
	v_lshlrev_b32_e32 v2, 5, v11
	v_mov_b32_e32 v3, v1
	v_lshlrev_b32_e32 v4, 3, v10
	v_mov_b32_e32 v5, v1
	s_waitcnt lgkmcnt(0)
	s_add_u32 s14, s14, 0x6000000
	s_addc_u32 s15, s15, 0
	v_lshl_add_u64 v[2:3], v[2:3], 3, s[14:15]
	v_lshl_add_u64 v[24:25], v[2:3], 0, v[4:5]
	global_load_dwordx4 v[176:179], v[24:25], off
	global_load_dwordx4 v[180:183], v[24:25], off offset:16
	global_load_dwordx4 v[184:187], v[24:25], off offset:32
	global_load_dwordx4 v[188:191], v[24:25], off offset:48
	s_waitcnt vmcnt(5)
	v_and_b32_e32 v9, 0xffff0000, v16
	s_waitcnt vmcnt(4)
	v_lshlrev_b32_e32 v8, 16, v20
	v_lshlrev_b32_e32 v4, 16, v16
	v_and_b32_e32 v5, 0xffff0000, v20
	v_mov_b32_e32 v29, v9
	v_mov_b32_e32 v28, v4
	v_lshlrev_b32_e32 v16, 16, v21
	s_waitcnt vmcnt(3)
	v_mov_b64_e32 v[2:3], v[176:177]
	v_mov_b32_e32 v26, v2
	s_waitcnt vmcnt(3)
	v_mov_b64_e32 v[10:11], v[178:179]
	v_mov_b32_e32 v27, v11
	v_pk_mov_b32 v[6:7], v[2:3], v[10:11] op_sel:[1,0]
	v_pk_mul_f32 v[26:27], v[26:27], v[8:9]
	v_mov_b32_e32 v9, v5
	v_pk_fma_f32 v[6:7], v[6:7], v[4:5], v[26:27]
	v_mov_b32_e32 v27, v10
	v_mov_b32_e32 v10, v3
	v_mov_b32_e32 v26, v2
	v_pk_mul_f32 v[2:3], v[10:11], v[8:9]
	v_and_b32_e32 v11, 0xffff0000, v17
	v_lshlrev_b32_e32 v10, 16, v17
	v_and_b32_e32 v17, 0xffff0000, v21
	v_pk_fma_f32 v[2:3], v[26:27], v[28:29], v[2:3] neg_lo:[0,0,1] neg_hi:[0,0,1]
	v_cvt_pk_bf16_f32 v6, v6, v7
	v_cvt_pk_bf16_f32 v2, v2, v3
	s_waitcnt vmcnt(2)
	v_mov_b64_e32 v[4:5], v[180:181]
	v_mov_b32_e32 v26, v4
	s_waitcnt vmcnt(2)
	v_mov_b64_e32 v[20:21], v[182:183]
	v_mov_b32_e32 v27, v20
	v_mov_b32_e32 v20, v5
	v_pk_mul_f32 v[4:5], v[20:21], v[10:11]
	s_nop 0
	v_pk_fma_f32 v[8:9], v[26:27], v[16:17], v[4:5]
	v_pk_mul_f32 v[4:5], v[20:21], v[16:17]
	v_and_b32_e32 v17, 0xffff0000, v18
	v_pk_fma_f32 v[4:5], v[26:27], v[10:11], v[4:5] neg_lo:[0,0,1] neg_hi:[0,0,1]
	v_lshlrev_b32_e32 v16, 16, v18
	v_and_b32_e32 v21, 0xffff0000, v22
	v_lshlrev_b32_e32 v20, 16, v22
	v_lshlrev_b32_e32 v18, 16, v23
	v_cvt_pk_bf16_f32 v3, v4, v5
	v_cvt_pk_bf16_f32 v7, v8, v9
	s_waitcnt vmcnt(1)
	v_mov_b64_e32 v[10:11], v[184:185]
	v_mov_b32_e32 v28, v10
	s_waitcnt vmcnt(1)
	v_mov_b64_e32 v[26:27], v[186:187]
	v_mov_b32_e32 v29, v26
	v_mov_b32_e32 v26, v11
	v_pk_mul_f32 v[10:11], v[26:27], v[16:17]
	s_nop 0
	v_pk_fma_f32 v[10:11], v[28:29], v[20:21], v[10:11]
	v_pk_mul_f32 v[20:21], v[26:27], v[20:21]
	v_and_b32_e32 v27, 0xffff0000, v19
	v_pk_fma_f32 v[16:17], v[28:29], v[16:17], v[20:21] neg_lo:[0,0,1] neg_hi:[0,0,1]
	v_lshlrev_b32_e32 v26, 16, v19
	v_and_b32_e32 v19, 0xffff0000, v23
	v_cvt_pk_bf16_f32 v4, v16, v17
	v_cvt_pk_bf16_f32 v8, v10, v11
	s_waitcnt vmcnt(0)
	v_mov_b64_e32 v[20:21], v[188:189]
	v_mov_b32_e32 v24, v20
	s_waitcnt vmcnt(0)
	v_mov_b64_e32 v[22:23], v[190:191]
	v_mov_b32_e32 v25, v22
	v_mov_b32_e32 v22, v21
	v_pk_mul_f32 v[20:21], v[22:23], v[26:27]
	s_nop 0
	v_pk_fma_f32 v[20:21], v[24:25], v[18:19], v[20:21]
	v_pk_mul_f32 v[18:19], v[22:23], v[18:19]
	v_cvt_pk_bf16_f32 v9, v20, v21
	v_pk_fma_f32 v[18:19], v[24:25], v[26:27], v[18:19] neg_lo:[0,0,1] neg_hi:[0,0,1]
	s_nop 0
	v_cvt_pk_bf16_f32 v5, v18, v19
	s_branch .LBB0_286

; __device__ __forceinline__ float bfs(short h) { return __uint_as_float(((unsigned)(u16)h) << 16); }
; __device__ __forceinline__ void phase_att_conv(PP p, const int g_wid, int layer) {
;     ...
;     {
;       int qi = row0 + fr;
;       if (qi < L) {
;         const u16* qp = Pac + (long)(base + qi) * 2304 + 1536 + qh * 64 + fq * 8;
;         bf16x8 a = *reinterpret_cast<const bf16x8*>(qp), b = *reinterpret_cast<const bf16x8*>(qp + 32);
;         const float2* cs = p->sincos + qi * 64 + 2 * fq * 8;
;         float t1[8], t2[8];
; #pragma unroll
;         for (int i = 0; i < 8; ++i) {
;           float2 c = cs[2 * i];
;           float x1 = bfs(a[i]), x2 = bfs(b[i]);
;           t1[i] = (x1 * c.x - x2 * c.y) * 0.18033688011112042f;
;           t2[i] = (x2 * c.x + x1 * c.y) * 0.18033688011112042f;
;         }
;         qa[0] = pack8(t1); qa[1] = pack8(t2);
.LBB0_300:
	v_or_b32_e32 v115, s7, v89
	v_lshlrev_b32_e32 v116, 4, v115
	v_or_b32_e32 v114, s6, v116
	v_or_b32_e32 v0, v114, v87
	v_cmp_gt_i32_e32 vcc, s3, v0
	v_mov_b32_e32 v66, 0
	v_mov_b32_e32 v67, 0
	v_mov_b32_e32 v68, 0
	v_mov_b32_e32 v69, 0
	v_mov_b32_e32 v70, 0
	v_mov_b32_e32 v71, 0
	v_mov_b32_e32 v72, 0
	v_mov_b32_e32 v73, 0
	s_and_saveexec_b64 s[8:9], vcc
	s_cbranch_execz .LBB0_302
	v_add_u32_e32 v2, s2, v0
	s_movk_i32 s7, 0x1200
	v_mad_i64_i32 v[6:7], s[10:11], v2, s7, v[82:83]
	v_readlane_b32 s10, v254, 0
	v_readlane_b32 s11, v254, 1
	global_load_dwordx4 v[2:5], v[6:7], off offset:3072
	s_nop 0
	global_load_dwordx4 v[6:9], v[6:7], off offset:3136
	s_load_dwordx2 s[10:11], s[10:11], 0xc0
	v_lshlrev_b32_e32 v10, 5, v0
	v_ashrrev_i32_e32 v11, 31, v10
	v_lshlrev_b32_e32 v0, 2, v74
	s_waitcnt lgkmcnt(0)
	s_add_u32 s10, s10, 0x6000000
	s_addc_u32 s11, s11, 0
	v_lshl_add_u64 v[10:11], v[10:11], 3, s[10:11]
	v_lshl_add_u64 v[18:19], v[10:11], 0, v[0:1]
	global_load_dwordx4 v[176:179], v[18:19], off
	global_load_dwordx4 v[180:183], v[18:19], off offset:16
	global_load_dwordx4 v[184:187], v[18:19], off offset:32
	global_load_dwordx4 v[188:191], v[18:19], off offset:48
	s_mov_b32 s10, 0x3e38aa3b
	s_waitcnt vmcnt(5)
	v_and_b32_e32 v17, 0xffff0000, v2
	s_waitcnt vmcnt(4)
	v_lshlrev_b32_e32 v16, 16, v6
	v_and_b32_e32 v15, 0xffff0000, v6
	v_lshlrev_b32_e32 v14, 16, v2
	v_mov_b32_e32 v25, v17
	v_mov_b32_e32 v24, v14
	s_waitcnt vmcnt(3)
	v_mov_b64_e32 v[12:13], v[176:177]
	v_mov_b32_e32 v22, v12
	s_waitcnt vmcnt(3)
	v_mov_b64_e32 v[20:21], v[178:179]
	v_mov_b32_e32 v23, v21
	v_pk_mov_b32 v[10:11], v[12:13], v[20:21] op_sel:[1,0]
	v_pk_mul_f32 v[22:23], v[22:23], v[16:17]
	v_mov_b32_e32 v17, v15
	v_pk_fma_f32 v[10:11], v[10:11], v[14:15], v[22:23]
	v_mov_b32_e32 v23, v20
	v_mov_b32_e32 v20, v13
	v_mov_b32_e32 v22, v12
	v_pk_mul_f32 v[12:13], v[20:21], v[16:17]
	v_and_b32_e32 v21, 0xffff0000, v7
	v_lshlrev_b32_e32 v20, 16, v7
	v_pk_fma_f32 v[12:13], v[22:23], v[24:25], v[12:13] neg_lo:[0,0,1] neg_hi:[0,0,1]
	v_and_b32_e32 v17, 0xffff0000, v3
	v_lshlrev_b32_e32 v16, 16, v3
	v_pk_mul_f32 v[10:11], v[10:11], s[10:11] op_sel_hi:[1,0]
	v_pk_mul_f32 v[12:13], v[12:13], s[10:11] op_sel_hi:[1,0]
	v_cvt_pk_bf16_f32 v66, v10, v11
	v_cvt_pk_bf16_f32 v70, v12, v13
	s_waitcnt vmcnt(2)
	v_mov_b64_e32 v[14:15], v[180:181]
	v_mov_b32_e32 v22, v14
	s_waitcnt vmcnt(2)
	v_mov_b64_e32 v[6:7], v[182:183]
	v_mov_b32_e32 v23, v6
	v_mov_b32_e32 v6, v15
	v_pk_mul_f32 v[2:3], v[6:7], v[16:17]
	v_pk_mul_f32 v[6:7], v[6:7], v[20:21]
	v_pk_fma_f32 v[2:3], v[22:23], v[20:21], v[2:3]
	v_pk_fma_f32 v[6:7], v[22:23], v[16:17], v[6:7] neg_lo:[0,0,1] neg_hi:[0,0,1]
	v_and_b32_e32 v17, 0xffff0000, v4
	v_lshlrev_b32_e32 v16, 16, v4
	v_and_b32_e32 v21, 0xffff0000, v8
	v_lshlrev_b32_e32 v20, 16, v8
	v_lshlrev_b32_e32 v4, 16, v9
	v_pk_mul_f32 v[2:3], v[2:3], s[10:11] op_sel_hi:[1,0]
	v_pk_mul_f32 v[6:7], v[6:7], s[10:11] op_sel_hi:[1,0]
	v_cvt_pk_bf16_f32 v67, v2, v3
	v_cvt_pk_bf16_f32 v71, v6, v7
	s_waitcnt vmcnt(1)
	v_mov_b64_e32 v[14:15], v[184:185]
	v_mov_b32_e32 v24, v14
	s_waitcnt vmcnt(1)
	v_mov_b64_e32 v[22:23], v[186:187]
	v_mov_b32_e32 v25, v22
	v_mov_b32_e32 v22, v15
	v_pk_mul_f32 v[14:15], v[22:23], v[16:17]
	s_nop 0
	v_pk_fma_f32 v[14:15], v[24:25], v[20:21], v[14:15]
	v_pk_mul_f32 v[20:21], v[22:23], v[20:21]
	v_and_b32_e32 v23, 0xffff0000, v5
	v_pk_fma_f32 v[16:17], v[24:25], v[16:17], v[20:21] neg_lo:[0,0,1] neg_hi:[0,0,1]
	v_lshlrev_b32_e32 v22, 16, v5
	v_and_b32_e32 v5, 0xffff0000, v9
	v_pk_mul_f32 v[14:15], v[14:15], s[10:11] op_sel_hi:[1,0]
	v_pk_mul_f32 v[16:17], v[16:17], s[10:11] op_sel_hi:[1,0]
	v_cvt_pk_bf16_f32 v68, v14, v15
	v_cvt_pk_bf16_f32 v72, v16, v17
	s_waitcnt vmcnt(0)
	v_mov_b64_e32 v[20:21], v[188:189]
	v_mov_b32_e32 v18, v20
	s_waitcnt vmcnt(0)
	v_mov_b64_e32 v[8:9], v[190:191]
	v_mov_b32_e32 v19, v8
	v_mov_b32_e32 v8, v21
	v_pk_mul_f32 v[20:21], v[8:9], v[22:23]
	s_nop 0
	v_pk_fma_f32 v[20:21], v[18:19], v[4:5], v[20:21]
	v_pk_mul_f32 v[4:5], v[8:9], v[4:5]
	v_pk_mul_f32 v[20:21], v[20:21], s[10:11] op_sel_hi:[1,0]
	v_pk_fma_f32 v[4:5], v[18:19], v[22:23], v[4:5] neg_lo:[0,0,1] neg_hi:[0,0,1]
	v_cvt_pk_bf16_f32 v69, v20, v21
	v_pk_mul_f32 v[4:5], v[4:5], s[10:11] op_sel_hi:[1,0]
	s_nop 0
	v_cvt_pk_bf16_f32 v73, v4, v5

; __device__ __forceinline__ float bfs(short h) { return __uint_as_float(((unsigned)(u16)h) << 16); }
; __device__ __forceinline__ void phase_att_conv(PP p, const int g_wid, int layer) {
;     ...
;         const float2* cs = p->sincos + j * 64 + 2 * i0;
;         float t1[8], t2[8];
; #pragma unroll
;         for (int i = 0; i < 8; ++i) {
;           float2 c = cs[2 * i];
;           float x1 = bfs(a[i]), x2 = bfs(b[i]);
;           t1[i] = x1 * c.x - x2 * c.y;
;           t2[i] = x2 * c.x + x1 * c.y;
;         }
.Lg3_nocopy:
	s_cmp_lg_u32 s34, 0x48
	s_cbranch_scc1 .Lg3_notab
	v_readlane_b32 s18, v254, 3
	s_lshl_b32 s18, s18, 9
	v_add_u32_e32 v200, s18, v142
	v_readlane_b32 s16, v254, 0
	v_readlane_b32 s17, v254, 1
	s_load_dwordx2 s[12:13], s[16:17], 0xc0
	s_load_dwordx2 s[14:15], s[16:17], 0xd8
	v_mov_b32_e32 v205, 0
	v_mov_b32_e32 v213, 0
	s_waitcnt lgkmcnt(0)
	s_add_u32 s12, s12, 0x6000000
	s_addc_u32 s13, s13, 0
	v_cmp_gt_u32_e32 vcc, 0x40100, v200
	s_and_saveexec_b64 s[16:17], vcc
	s_cbranch_execz .Lg3_tab0
	v_lshrrev_b32_e32 v201, 4, v200
	v_and_b32_e32 v202, 15, v200
	v_lshlrev_b32_e32 v201, 9, v201
	v_lshl_add_u32 v204, v202, 5, v201
	v_lshl_add_u64 v[206:207], s[14:15], 0, v[204:205]
	global_load_dwordx2 v[208:209], v[206:207], off
	global_load_dwordx2 v[210:211], v[206:207], off offset:16
	v_lshlrev_b32_e32 v212, 4, v200
	v_lshl_add_u64 v[214:215], s[12:13], 0, v[212:213]
	s_waitcnt vmcnt(0)
	global_store_dwordx4 v[214:215], v[208:211], off
.Lg3_tab0:
	s_or_b64 exec, exec, s[16:17]
	v_add_u32_e32 v200, 0x20000, v200
	v_cmp_gt_u32_e32 vcc, 0x40100, v200
	s_and_saveexec_b64 s[16:17], vcc
	s_cbranch_execz .Lg3_tab1
	v_lshrrev_b32_e32 v201, 4, v200
	v_and_b32_e32 v202, 15, v200
	v_lshlrev_b32_e32 v201, 9, v201
	v_lshl_add_u32 v204, v202, 5, v201
	v_lshl_add_u64 v[206:207], s[14:15], 0, v[204:205]
	global_load_dwordx2 v[208:209], v[206:207], off
	global_load_dwordx2 v[210:211], v[206:207], off offset:16
	v_lshlrev_b32_e32 v212, 4, v200
	v_lshl_add_u64 v[214:215], s[12:13], 0, v[212:213]
	s_waitcnt vmcnt(0)
	global_store_dwordx4 v[214:215], v[208:211], off

; __device__ __forceinline__ void phase_att_conv(PP p, const int g_wid, int layer) {
;     ...
;         const float2* cs = p->sincos + j * 64 + 2 * i0;
;         float t1[8], t2[8];
; #pragma unroll
;         for (int i = 0; i < 8; ++i) {
;           float2 c = cs[2 * i];
.Lg3_tab2:
	s_or_b64 exec, exec, s[16:17]
	v_add_u32_e32 v200, 0x20000, v200
